# dil item epilogue: eight LDS reads of the O rows issued together, stores behind counted lgkmcnt waits
# baseline (speedup 1.0000x reference)
.LBB0_336:
	s_or_b64 exec, exec, s[36:37]
	s_lshl_b64 s[2:3], s[46:47], 25
	s_add_u32 s2, s8, s2
	s_addc_u32 s3, s9, s3
	s_lshl_b64 s[0:1], s[0:1], 21
	s_add_u32 s0, s2, s0
	s_addc_u32 s1, s3, s1
	s_lshl_b32 s2, s18, 1
	v_xor_b32_e32 v0, v179, v184
	s_add_u32 s0, s0, s2
	v_lshlrev_b32_e32 v0, 4, v0
	s_addc_u32 s1, s1, 0
	v_add_u32_e32 v10, s27, v50
	v_and_b32_e32 v0, 0x70, v0
	v_lshl_add_u64 v[6:7], s[0:1], 0, v[0:1]
	v_lshl_add_u32 v73, v179, 7, v10
	ds_read_b128 v[76:79], v73
	ds_read_b128 v[80:83], v73 offset:1024
	ds_read_b128 v[84:87], v73 offset:2048
	ds_read_b128 v[88:91], v73 offset:3072
	ds_read_b128 v[92:95], v73 offset:4096
	ds_read_b128 v[96:99], v73 offset:5120
	ds_read_b128 v[100:103], v73 offset:6144
	ds_read_b128 v[104:107], v73 offset:7168
	v_lshlrev_b32_e32 v74, s15, v191
	v_add_u32_e32 v124, s16, v74
	v_ashrrev_i32_e32 v125, 31, v124
	v_lshlrev_b64 v[124:125], 10, v[124:125]
	v_lshl_add_u64 v[124:125], v[6:7], 0, v[124:125]
	v_add_u32_e32 v74, 8, v191
	v_lshlrev_b32_e32 v74, s15, v74
	v_add_u32_e32 v126, s16, v74
	v_ashrrev_i32_e32 v127, 31, v126
	v_lshlrev_b64 v[126:127], 10, v[126:127]
	v_lshl_add_u64 v[126:127], v[6:7], 0, v[126:127]
	v_add_u32_e32 v74, 16, v191
	v_lshlrev_b32_e32 v74, s15, v74
	v_add_u32_e32 v128, s16, v74
	v_ashrrev_i32_e32 v129, 31, v128
	v_lshlrev_b64 v[128:129], 10, v[128:129]
	v_lshl_add_u64 v[128:129], v[6:7], 0, v[128:129]
	v_add_u32_e32 v74, 24, v191
	v_lshlrev_b32_e32 v74, s15, v74
	v_add_u32_e32 v130, s16, v74
	v_ashrrev_i32_e32 v131, 31, v130
	v_lshlrev_b64 v[130:131], 10, v[130:131]
	v_lshl_add_u64 v[130:131], v[6:7], 0, v[130:131]
	v_add_u32_e32 v74, 32, v191
	v_lshlrev_b32_e32 v74, s15, v74
	v_add_u32_e32 v132, s16, v74
	v_ashrrev_i32_e32 v133, 31, v132
	v_lshlrev_b64 v[132:133], 10, v[132:133]
	v_lshl_add_u64 v[132:133], v[6:7], 0, v[132:133]
	v_add_u32_e32 v74, 40, v191
	v_lshlrev_b32_e32 v74, s15, v74
	v_add_u32_e32 v134, s16, v74
	v_ashrrev_i32_e32 v135, 31, v134
	v_lshlrev_b64 v[134:135], 10, v[134:135]
	v_lshl_add_u64 v[134:135], v[6:7], 0, v[134:135]
	v_add_u32_e32 v74, 48, v191
	v_lshlrev_b32_e32 v74, s15, v74
	v_add_u32_e32 v136, s16, v74
	v_ashrrev_i32_e32 v137, 31, v136
	v_lshlrev_b64 v[136:137], 10, v[136:137]
	v_lshl_add_u64 v[136:137], v[6:7], 0, v[136:137]
	v_add_u32_e32 v74, 56, v191
	v_lshlrev_b32_e32 v74, s15, v74
	v_add_u32_e32 v138, s16, v74
	v_ashrrev_i32_e32 v139, 31, v138
	v_lshlrev_b64 v[138:139], 10, v[138:139]
	v_lshl_add_u64 v[138:139], v[6:7], 0, v[138:139]
	s_waitcnt lgkmcnt(7)
	global_store_dwordx4 v[124:125], v[76:79], off
	s_waitcnt lgkmcnt(6)
	global_store_dwordx4 v[126:127], v[80:83], off
	s_waitcnt lgkmcnt(5)
	global_store_dwordx4 v[128:129], v[84:87], off
	s_waitcnt lgkmcnt(4)
	global_store_dwordx4 v[130:131], v[88:91], off
	s_waitcnt lgkmcnt(3)
	global_store_dwordx4 v[132:133], v[92:95], off
	s_waitcnt lgkmcnt(2)
	global_store_dwordx4 v[134:135], v[96:99], off
	s_waitcnt lgkmcnt(1)
	global_store_dwordx4 v[136:137], v[100:103], off
	s_waitcnt lgkmcnt(0)
	global_store_dwordx4 v[138:139], v[104:107], off
	s_add_i32 s14, s14, s42
	s_cmpk_gt_i32 s14, 0x2fff
	s_cbranch_scc1 .LBB0_370

.Lepix_branch:
	s_branch .LBB0_521
	s_nop 0
	s_nop 0
	s_nop 0
	s_nop 0
	s_nop 0
	s_nop 0
	s_nop 0
	s_nop 0
	s_nop 0
	s_nop 0
	s_nop 0
	s_nop 0
	s_nop 0
